# P7 last-round half-unit K-loop rebalanced: 16 MFMAs in each of the 4 segments (bj=1 block deferred to next SP1, B fragments double-buffered in dead accumulators)
# speedup vs baseline: 1.0022x; 1.0022x over previous
; #define PG8_STAGE(bufoff, gbase, voff) do { _Pragma("unroll") for (int _i = 0; _i < 2; ++_i) \
;         __builtin_amdgcn_global_load_lds((const unsigned*)((const char*)(gbase) + (voff)[_i]), (PG8_LAS unsigned*)(lds + (bufoff) + ldsw + _i * 8192), 16, 0, 0); } while (0)
; #define PG8_LDA(dst, b, h) do { _Pragma("unroll") for (int m = 0; m < 4; ++m) _Pragma("unroll") for (int k = 0; k < 2; ++k) dst[m][k] = *(const PG8_LAS bf16x8*)(lds + PG8_SA(b, h) + aoff + m * 2048 + k * 1024); } while (0)
; #define PG8_LDB(dst, b, h) do { _Pragma("unroll") for (int n = 0; n < 2; ++n) _Pragma("unroll") for (int k = 0; k < 2; ++k) dst[n][k] = *(const PG8_LAS bf16x8*)(lds + PG8_SB(b, h) + boff + n * 2048 + k * 1024); } while (0)
; #define PG8_MMA(ai, bj, At, Bt) do { __builtin_amdgcn_s_setprio(1); _Pragma("unroll") for (int m = 0; m < 4; ++m) _Pragma("unroll") for (int n = 0; n < 2; ++n) _Pragma("unroll") for (int k = 0; k < 2; ++k) \
;         acc[ai][bj][m][n] = __builtin_amdgcn_mfma_f32_16x16x32_bf16(Bt[n][k], At[m][k], acc[ai][bj][m][n], 0, 0, 0); __builtin_amdgcn_s_setprio(0); } while (0)
; template <class Epi, class Sched, bool ALIGN_EPI = false, bool SP2 = false>
; __device__ __forceinline__ void gemm_phase(PG8_LAS unsigned char* lds, const Gemm g, const Sched& S, const Epi& E) {
;     ...
;             if constexpr (SP2) {
;             PG8_LDB(B0, 0, 0); PG8_LDB(B1, 0, 1); PG8_SCHED; PG8_LDA(At, 0, 0); PG8_STAGE(PG8_SA(1, 1), a1 + hstepA, voffA);
;             PG8_WAIT_V(8); PG8_WAIT_L(0); PG8_BAR; PG8_MMA(0, 0, At, B0); PG8_MMA(0, 1, At, B1); PG8_BAR; PG8_SCHED;
;             PG8_LDA(At, 0, 1); PG8_STAGE(PG8_SB(0, 0), b2, voffB); PG8_STAGE(PG8_SB(0, 1), b2 + hstepB, voffB); PG8_STAGE(PG8_SA(0, 0), a2, voffA);
;             PG8_WAIT_V(8); PG8_WAIT_L(0); PG8_BAR; PG8_MMA(1, 0, At, B0); PG8_MMA(1, 1, At, B1); PG8_BAR; PG8_SCHED;
;             PG8_LDB(B0, 1, 0); PG8_LDB(B1, 1, 1); PG8_SCHED; PG8_LDA(At, 1, 0); PG8_STAGE(PG8_SA(0, 1), a2 + hstepA, voffA);
;             PG8_WAIT_V(8); PG8_WAIT_L(0); PG8_BAR; PG8_MMA(0, 0, At, B0); PG8_MMA(0, 1, At, B1); PG8_BAR; PG8_SCHED;
;             PG8_LDA(At, 1, 1); PG8_STAGE(PG8_SB(1, 0), b3, voffB); PG8_STAGE(PG8_SB(1, 1), b3 + hstepB, voffB); PG8_STAGE(PG8_SA(1, 0), a3, voffA);
;             PG8_WAIT_V(8); PG8_WAIT_L(0); PG8_BAR; PG8_MMA(1, 0, At, B0); PG8_MMA(1, 1, At, B1); PG8_BAR; PG8_SCHED;
.Lp7h_entry:
	v_mov_b32_e32 v184, 0
	v_mov_b32_e32 v185, 0
	v_mov_b32_e32 v186, 0
	v_mov_b32_e32 v187, 0
	v_mov_b32_e32 v188, 0
	v_mov_b32_e32 v189, 0
	v_mov_b32_e32 v190, 0
	v_mov_b32_e32 v191, 0
	v_mov_b32_e32 v192, 0
	v_mov_b32_e32 v193, 0
	v_mov_b32_e32 v194, 0
	v_mov_b32_e32 v195, 0
	v_mov_b32_e32 v196, 0
	v_mov_b32_e32 v197, 0
	v_mov_b32_e32 v198, 0
	v_mov_b32_e32 v199, 0
	v_mov_b32_e32 v200, 0
	v_mov_b32_e32 v201, 0
	v_mov_b32_e32 v202, 0
	v_mov_b32_e32 v203, 0
	v_mov_b32_e32 v204, 0
	v_mov_b32_e32 v205, 0
	v_mov_b32_e32 v206, 0
	v_mov_b32_e32 v207, 0
	v_mov_b32_e32 v208, 0
	v_mov_b32_e32 v209, 0
	v_mov_b32_e32 v210, 0
	v_mov_b32_e32 v211, 0
	v_mov_b32_e32 v212, 0
	v_mov_b32_e32 v213, 0
	v_mov_b32_e32 v214, 0
	v_mov_b32_e32 v215, 0
	v_mov_b32_e32 v80, 0
	v_mov_b32_e32 v81, 0
	v_mov_b32_e32 v82, 0
	v_mov_b32_e32 v83, 0
	v_mov_b32_e32 v84, 0
	v_mov_b32_e32 v85, 0
	v_mov_b32_e32 v86, 0
	v_mov_b32_e32 v87, 0
	v_mov_b32_e32 v88, 0
	v_mov_b32_e32 v89, 0
	v_mov_b32_e32 v90, 0
	v_mov_b32_e32 v91, 0
	v_mov_b32_e32 v92, 0
	v_mov_b32_e32 v93, 0
	v_mov_b32_e32 v94, 0
	v_mov_b32_e32 v95, 0
.Lp7h_loop:
	ds_read_b128 v[144:147], v151
	ds_read_b128 v[156:159], v151 offset:1024
	ds_read_b128 v[160:163], v151 offset:2048
	ds_read_b128 v[164:167], v151 offset:3072
	ds_read_b128 v[168:171], v152
	ds_read_b128 v[172:175], v152 offset:1024
	ds_read_b128 v[176:179], v152 offset:2048
	ds_read_b128 v[180:183], v152 offset:3072
	s_add_u32 s34, s30, 0xfff80080
	s_addc_u32 s35, s31, -1
	s_cmp_eq_u32 s62, 28
	s_cselect_b32 s39, s21, s35
	s_cselect_b32 s38, s25, s34
	s_cselect_b32 s35, s23, s61
	s_cselect_b32 s34, s59, s60
	v_lshl_add_u64 v[216:217], s[30:31], 0, v[136:137]
	s_add_i32 m0, s6, 0xc000
	global_load_lds_dwordx4 v[216:217], off
	v_lshl_add_u64 v[216:217], s[30:31], 0, v[138:139]
	s_add_i32 m0, s6, 0xe000
	s_nop 0
	global_load_lds_dwordx4 v[216:217], off
	s_waitcnt vmcnt(6)
	s_waitcnt lgkmcnt(0)
	s_barrier
	s_setprio 1
	s_waitcnt lgkmcnt(0)
	v_mfma_f32_16x16x32_bf16 v[56:59], v[80:83], v[184:187], v[56:59]
	v_mfma_f32_16x16x32_bf16 v[48:51], v[88:91], v[184:187], v[48:51]
	v_mfma_f32_16x16x32_bf16 v[40:43], v[80:83], v[192:195], v[40:43]
	v_mfma_f32_16x16x32_bf16 v[32:35], v[88:91], v[192:195], v[32:35]
	v_mfma_f32_16x16x32_bf16 v[24:27], v[80:83], v[200:203], v[24:27]
	v_mfma_f32_16x16x32_bf16 v[16:19], v[88:91], v[200:203], v[16:19]
	v_mfma_f32_16x16x32_bf16 v[8:11], v[80:83], v[208:211], v[8:11]
	v_mfma_f32_16x16x32_bf16 v[0:3], v[88:91], v[208:211], v[0:3]
	v_mfma_f32_16x16x32_bf16 v[56:59], v[84:87], v[188:191], v[56:59]
	v_mfma_f32_16x16x32_bf16 v[48:51], v[92:95], v[188:191], v[48:51]
	v_mfma_f32_16x16x32_bf16 v[40:43], v[84:87], v[196:199], v[40:43]
	v_mfma_f32_16x16x32_bf16 v[32:35], v[92:95], v[196:199], v[32:35]
	v_mfma_f32_16x16x32_bf16 v[24:27], v[84:87], v[204:207], v[24:27]
	v_mfma_f32_16x16x32_bf16 v[16:19], v[92:95], v[204:207], v[16:19]
	v_mfma_f32_16x16x32_bf16 v[8:11], v[84:87], v[212:215], v[8:11]
	v_mfma_f32_16x16x32_bf16 v[0:3], v[92:95], v[212:215], v[0:3]
	s_setprio 0
	s_setprio 1
	s_setprio 0
	s_barrier
	s_add_i32 s63, s53, s4
	v_lshl_add_u64 v[216:217], s[34:35], 0, v[132:133]
	s_mov_b32 m0, s63
	ds_read_b128 v[184:187], v153 offset:16384
	ds_read_b128 v[188:191], v153 offset:17408
	ds_read_b128 v[192:195], v153 offset:18432
	ds_read_b128 v[196:199], v153 offset:19456
	ds_read_b128 v[200:203], v153 offset:20480
	ds_read_b128 v[204:207], v153 offset:21504
	ds_read_b128 v[208:211], v153 offset:22528
	ds_read_b128 v[212:215], v153 offset:23552
	global_load_lds_dwordx4 v[216:217], off
	s_add_i32 m0, s63, 0x2000
	s_add_u32 s64, s34, 0x80000
	v_lshl_add_u64 v[218:219], s[34:35], 0, v[128:129]
	s_addc_u32 s65, s35, 0
	s_add_i32 s63, s54, s4
	global_load_lds_dwordx4 v[218:219], off
	v_lshl_add_u64 v[220:221], s[64:65], 0, v[132:133]
	s_mov_b32 m0, s63
	v_lshl_add_u64 v[222:223], s[38:39], 0, v[130:131]
	global_load_lds_dwordx4 v[220:221], off
	v_lshl_add_u64 v[220:221], s[64:65], 0, v[128:129]
	s_add_i32 m0, s63, 0x2000
	s_nop 0
	global_load_lds_dwordx4 v[220:221], off
	v_lshl_add_u64 v[220:221], s[38:39], 0, v[134:135]
	s_mov_b32 m0, s6
	s_nop 0
	s_mov_b32 m0, s7
	s_nop 0
	s_waitcnt vmcnt(6)
	s_waitcnt lgkmcnt(0)
	s_barrier
	s_setprio 1
	s_waitcnt lgkmcnt(0)
	v_mfma_f32_16x16x32_bf16 v[60:63], v[144:147], v[184:187], v[60:63]
	v_mfma_f32_16x16x32_bf16 v[52:55], v[160:163], v[184:187], v[52:55]
	v_mfma_f32_16x16x32_bf16 v[44:47], v[144:147], v[192:195], v[44:47]
	v_mfma_f32_16x16x32_bf16 v[36:39], v[160:163], v[192:195], v[36:39]
	v_mfma_f32_16x16x32_bf16 v[28:31], v[144:147], v[200:203], v[28:31]
	v_mfma_f32_16x16x32_bf16 v[20:23], v[160:163], v[200:203], v[20:23]
	v_mfma_f32_16x16x32_bf16 v[12:15], v[144:147], v[208:211], v[12:15]
	v_mfma_f32_16x16x32_bf16 v[4:7], v[160:163], v[208:211], v[4:7]
	v_mfma_f32_16x16x32_bf16 v[60:63], v[156:159], v[188:191], v[60:63]
	v_mfma_f32_16x16x32_bf16 v[52:55], v[164:167], v[188:191], v[52:55]
	v_mfma_f32_16x16x32_bf16 v[44:47], v[156:159], v[196:199], v[44:47]
	v_mfma_f32_16x16x32_bf16 v[36:39], v[164:167], v[196:199], v[36:39]
	v_mfma_f32_16x16x32_bf16 v[28:31], v[156:159], v[204:207], v[28:31]
	v_mfma_f32_16x16x32_bf16 v[20:23], v[164:167], v[204:207], v[20:23]
	v_mfma_f32_16x16x32_bf16 v[12:15], v[156:159], v[212:215], v[12:15]
	v_mfma_f32_16x16x32_bf16 v[4:7], v[164:167], v[212:215], v[4:7]
	s_setprio 0
	s_setprio 1
	s_setprio 0
	s_barrier
; #define PG8_STAGE(bufoff, gbase, voff) do { _Pragma("unroll") for (int _i = 0; _i < 2; ++_i) \
;         __builtin_amdgcn_global_load_lds((const unsigned*)((const char*)(gbase) + (voff)[_i]), (PG8_LAS unsigned*)(lds + (bufoff) + ldsw + _i * 8192), 16, 0, 0); } while (0)
; #define PG8_LDA(dst, b, h) do { _Pragma("unroll") for (int m = 0; m < 4; ++m) _Pragma("unroll") for (int k = 0; k < 2; ++k) dst[m][k] = *(const PG8_LAS bf16x8*)(lds + PG8_SA(b, h) + aoff + m * 2048 + k * 1024); } while (0)
; #define PG8_WAIT_V(n) asm volatile("s_waitcnt vmcnt(" #n ")" ::: "memory")
; #define PG8_BAR __builtin_amdgcn_s_barrier()
; template <class Epi, class Sched, bool ALIGN_EPI = false, bool SP2 = false>
; __device__ __forceinline__ void gemm_phase(PG8_LAS unsigned char* lds, const Gemm g, const Sched& S, const Epi& E) {
;     ...
;         for (int t = 0; t < nt; t += 2) {
;             const bool last = (t == nt - 2);
;             if constexpr (Epi::HAS_MID) { if (t == E.mid_t) E.mid(acc, cur, wr, wc, fr, fq); }
;             const char* a1 = cA + (size_t)(t + 1) * kstep;
;             const char* a2 = last ? nA : cA + (size_t)(t + 2) * kstep; const char* b2 = last ? nB : cB + (size_t)(t + 2) * kstep;
;             const char* a3 = a2 + kstep; const char* b3 = b2 + kstep;
;             if (last && has_next) S.a_ready(nxt);
;             if constexpr (SP2) {
;             PG8_LDB(B0, 0, 0); PG8_LDB(B1, 0, 1); PG8_SCHED; PG8_LDA(At, 0, 0); PG8_STAGE(PG8_SA(1, 1), a1 + hstepA, voffA);
;             PG8_WAIT_V(8); PG8_WAIT_L(0); PG8_BAR; PG8_MMA(0, 0, At, B0); PG8_MMA(0, 1, At, B1); PG8_BAR; PG8_SCHED;
;             PG8_LDA(At, 0, 1); PG8_STAGE(PG8_SB(0, 0), b2, voffB); PG8_STAGE(PG8_SB(0, 1), b2 + hstepB, voffB); PG8_STAGE(PG8_SA(0, 0), a2, voffA);
;             PG8_WAIT_V(8); PG8_WAIT_L(0); PG8_BAR; PG8_MMA(1, 0, At, B0); PG8_MMA(1, 1, At, B1); PG8_BAR; PG8_SCHED;
;             PG8_LDB(B0, 1, 0); PG8_LDB(B1, 1, 1); PG8_SCHED; PG8_LDA(At, 1, 0); PG8_STAGE(PG8_SA(0, 1), a2 + hstepA, voffA);
;             PG8_WAIT_V(8); PG8_WAIT_L(0); PG8_BAR; PG8_MMA(0, 0, At, B0); PG8_MMA(0, 1, At, B1); PG8_BAR; PG8_SCHED;
;             PG8_LDA(At, 1, 1); PG8_STAGE(PG8_SB(1, 0), b3, voffB); PG8_STAGE(PG8_SB(1, 1), b3 + hstepB, voffB); PG8_STAGE(PG8_SA(1, 0), a3, voffA);
;             PG8_WAIT_V(8); PG8_WAIT_L(0); PG8_BAR; PG8_MMA(1, 0, At, B0); PG8_MMA(1, 1, At, B1); PG8_BAR; PG8_SCHED;
	s_add_i32 s63, 0, 0x18000
	v_add_u32_e32 v155, s63, v150
	s_add_i32 s64, 0, 0x1c000
	ds_read_b128 v[64:67], v155
	ds_read_b128 v[68:71], v155 offset:1024
	ds_read_b128 v[72:75], v155 offset:2048
	ds_read_b128 v[76:79], v155 offset:3072
	v_add_u32_e32 v155, s64, v150
	ds_read_b128 v[80:83], v155
	ds_read_b128 v[84:87], v155 offset:1024
	ds_read_b128 v[88:91], v155 offset:2048
	ds_read_b128 v[92:95], v155 offset:3072
	s_add_u32 s38, s38, 0x80000
	s_addc_u32 s39, s39, 0
	s_mov_b32 m0, s41
	v_lshl_add_u64 v[224:225], s[38:39], 0, v[134:135]
	global_load_lds_dwordx4 v[224:225], off
	v_lshl_add_u64 v[224:225], s[38:39], 0, v[130:131]
	s_mov_b32 m0, s42
	s_nop 0
	global_load_lds_dwordx4 v[224:225], off
	s_waitcnt vmcnt(6)
	s_waitcnt lgkmcnt(0)
	s_barrier
	s_setprio 1
	s_waitcnt lgkmcnt(0)
	v_mfma_f32_16x16x32_bf16 v[56:59], v[168:171], v[184:187], v[56:59]
	v_mfma_f32_16x16x32_bf16 v[48:51], v[176:179], v[184:187], v[48:51]
	v_mfma_f32_16x16x32_bf16 v[40:43], v[168:171], v[192:195], v[40:43]
	v_mfma_f32_16x16x32_bf16 v[32:35], v[176:179], v[192:195], v[32:35]
	v_mfma_f32_16x16x32_bf16 v[24:27], v[168:171], v[200:203], v[24:27]
	v_mfma_f32_16x16x32_bf16 v[16:19], v[176:179], v[200:203], v[16:19]
	v_mfma_f32_16x16x32_bf16 v[8:11], v[168:171], v[208:211], v[8:11]
	v_mfma_f32_16x16x32_bf16 v[0:3], v[176:179], v[208:211], v[0:3]
	v_mfma_f32_16x16x32_bf16 v[56:59], v[172:175], v[188:191], v[56:59]
	v_mfma_f32_16x16x32_bf16 v[48:51], v[180:183], v[188:191], v[48:51]
	v_mfma_f32_16x16x32_bf16 v[40:43], v[172:175], v[196:199], v[40:43]
	v_mfma_f32_16x16x32_bf16 v[32:35], v[180:183], v[196:199], v[32:35]
	v_mfma_f32_16x16x32_bf16 v[24:27], v[172:175], v[204:207], v[24:27]
	v_mfma_f32_16x16x32_bf16 v[16:19], v[180:183], v[204:207], v[16:19]
	v_mfma_f32_16x16x32_bf16 v[8:11], v[172:175], v[212:215], v[8:11]
	v_mfma_f32_16x16x32_bf16 v[0:3], v[180:183], v[212:215], v[0:3]
	s_setprio 0
	s_setprio 1
	s_setprio 0
	s_barrier
	s_add_i32 s38, s63, s4
	v_lshl_add_u64 v[216:217], v[216:217], 0, s[16:17]
	s_mov_b32 m0, s38
	ds_read_b128 v[184:187], v153 offset:49152
	ds_read_b128 v[188:191], v153 offset:50176
	ds_read_b128 v[192:195], v153 offset:51200
	ds_read_b128 v[196:199], v153 offset:52224
	ds_read_b128 v[200:203], v153 offset:53248
	ds_read_b128 v[204:207], v153 offset:54272
	ds_read_b128 v[208:211], v153 offset:55296
	ds_read_b128 v[212:215], v153 offset:56320
	global_load_lds_dwordx4 v[216:217], off
	s_add_i32 m0, s38, 0x2000
	s_add_u32 s34, s34, 0x80080
	v_lshl_add_u64 v[216:217], v[218:219], 0, s[16:17]
	s_addc_u32 s35, s35, 0
	s_add_i32 s38, s64, s4
	global_load_lds_dwordx4 v[216:217], off
	v_lshl_add_u64 v[216:217], s[34:35], 0, v[132:133]
	s_mov_b32 m0, s38
	s_nop 0
	global_load_lds_dwordx4 v[216:217], off
	v_lshl_add_u64 v[216:217], s[34:35], 0, v[128:129]
	s_add_i32 m0, s38, 0x2000
	s_nop 0
	global_load_lds_dwordx4 v[216:217], off
	v_lshl_add_u64 v[216:217], v[220:221], 0, s[16:17]
	s_mov_b32 m0, s46
	s_nop 0
	v_lshl_add_u64 v[216:217], v[222:223], 0, s[16:17]
	s_mov_b32 m0, s47
	s_nop 0
	s_waitcnt vmcnt(6)
	s_waitcnt lgkmcnt(0)
	s_barrier
	s_setprio 1
	s_waitcnt lgkmcnt(0)
	v_mfma_f32_16x16x32_bf16 v[60:63], v[64:67], v[184:187], v[60:63]
	v_mfma_f32_16x16x32_bf16 v[52:55], v[72:75], v[184:187], v[52:55]
	v_mfma_f32_16x16x32_bf16 v[44:47], v[64:67], v[192:195], v[44:47]
	v_mfma_f32_16x16x32_bf16 v[36:39], v[72:75], v[192:195], v[36:39]
	v_mfma_f32_16x16x32_bf16 v[28:31], v[64:67], v[200:203], v[28:31]
	v_mfma_f32_16x16x32_bf16 v[20:23], v[72:75], v[200:203], v[20:23]
	v_mfma_f32_16x16x32_bf16 v[12:15], v[64:67], v[208:211], v[12:15]
	v_mfma_f32_16x16x32_bf16 v[4:7], v[72:75], v[208:211], v[4:7]
	v_mfma_f32_16x16x32_bf16 v[60:63], v[68:71], v[188:191], v[60:63]
	v_mfma_f32_16x16x32_bf16 v[52:55], v[76:79], v[188:191], v[52:55]
	v_mfma_f32_16x16x32_bf16 v[44:47], v[68:71], v[196:199], v[44:47]
	v_mfma_f32_16x16x32_bf16 v[36:39], v[76:79], v[196:199], v[36:39]
	v_mfma_f32_16x16x32_bf16 v[28:31], v[68:71], v[204:207], v[28:31]
	v_mfma_f32_16x16x32_bf16 v[20:23], v[76:79], v[204:207], v[20:23]
	v_mfma_f32_16x16x32_bf16 v[12:15], v[68:71], v[212:215], v[12:15]
	v_mfma_f32_16x16x32_bf16 v[4:7], v[76:79], v[212:215], v[4:7]
	s_setprio 0
	s_setprio 1
	s_setprio 0
	s_barrier
	s_add_i32 s62, s62, 2
	s_add_u32 s30, s30, 0x100
	s_addc_u32 s31, s31, 0
	s_add_u32 s60, s60, 0x100
	s_addc_u32 s61, s61, 0
	s_cmp_gt_u32 s62, 29
	s_cbranch_scc0 .Lp7h_loop
	v_mfma_f32_16x16x32_bf16 v[56:59], v[80:83], v[184:187], v[56:59]
	v_mfma_f32_16x16x32_bf16 v[48:51], v[88:91], v[184:187], v[48:51]
	v_mfma_f32_16x16x32_bf16 v[40:43], v[80:83], v[192:195], v[40:43]
	v_mfma_f32_16x16x32_bf16 v[32:35], v[88:91], v[192:195], v[32:35]
	v_mfma_f32_16x16x32_bf16 v[24:27], v[80:83], v[200:203], v[24:27]
	v_mfma_f32_16x16x32_bf16 v[16:19], v[88:91], v[200:203], v[16:19]
	v_mfma_f32_16x16x32_bf16 v[8:11], v[80:83], v[208:211], v[8:11]
	v_mfma_f32_16x16x32_bf16 v[0:3], v[88:91], v[208:211], v[0:3]
	v_mfma_f32_16x16x32_bf16 v[56:59], v[84:87], v[188:191], v[56:59]
	v_mfma_f32_16x16x32_bf16 v[48:51], v[92:95], v[188:191], v[48:51]
	v_mfma_f32_16x16x32_bf16 v[40:43], v[84:87], v[196:199], v[40:43]
	v_mfma_f32_16x16x32_bf16 v[32:35], v[92:95], v[196:199], v[32:35]
	v_mfma_f32_16x16x32_bf16 v[24:27], v[84:87], v[204:207], v[24:27]
	v_mfma_f32_16x16x32_bf16 v[16:19], v[92:95], v[204:207], v[16:19]
	v_mfma_f32_16x16x32_bf16 v[8:11], v[84:87], v[212:215], v[8:11]
	v_mfma_f32_16x16x32_bf16 v[0:3], v[92:95], v[212:215], v[0:3]
	s_nop 15
	s_nop 15
	s_branch .Lp7_after_loop
